# GEMM in-projection epilogue: next-tile rowss wait moved behind the 16 stores (vmcnt(16) at its first consumer), on the static-priority version
# speedup vs baseline: 1.0095x; 1.0095x over previous
; __device__ __forceinline__ unsigned cvt_pk_bf16(float lo, float hi) { unsigned r; asm volatile("v_cvt_pk_bf16_f32 %0, %1, %2" : "=v"(r) : "v"(lo), "v"(hi)); return r; }
;     __device__ __forceinline__ void operator()(const f32x4 (&acc)[2][2][4][2], const Unit& u, int wr, int wc, int fr, int fq, int slot, bool has_next, const Unit& nxt) const {
;     ...
;         const bool fill = has_next && threadIdx.x < 256;
;         unsigned long long ssn = 0; if (fill) ssn = rowss[nxt.pm * BM + threadIdx.x];
;         float rsv[8];
; #pragma unroll
;         for (int i = 0; i < 8; ++i) rsv[i] = tab[slot * 256 + wr * 64 + fr + (i >> 2) * HALF + (i & 3) * 16];
; #pragma unroll
;         for (int ai = 0; ai < 2; ++ai)
; #pragma unroll
;             for (int m = 0; m < 4; ++m) { const int row = row0 + ai * HALF + m * 16; const float rs = rsv[ai * 4 + m];
;                 bf16_t* rowp = O + (size_t)row * ldc + col0;
; #pragma unroll
;                 for (int bj = 0; bj < 2; ++bj) { const f32x4 v0 = acc[ai][bj][m][0] * rs, v1 = acc[ai][bj][m][1] * rs;
;                     u32x4 w; w.x = cvt_pk_bf16(v0[0], v0[1]); w.y = cvt_pk_bf16(v0[2], v0[3]); w.z = cvt_pk_bf16(v1[0], v1[1]); w.w = cvt_pk_bf16(v1[2], v1[3]);
;                     *(u32x4*)(rowp + bj * HALF) = w; } }
.LBB0_191:
	s_and_b64 s[28:29], s[0:1], s[2:3]
	v_mov_b32_e32 v138, 0x358637bd
	s_and_saveexec_b64 s[30:31], s[28:29]
	s_cbranch_execz .LBB0_193
	v_lshl_or_b32 v138, s14, 8, v0
	v_lshl_add_u64 v[244:245], v[138:139], 3, s[18:19]
	global_load_dwordx2 v[244:245], v[244:245], off
.LBB0_193:
	s_or_b64 exec, exec, s[30:31]
	s_and_b32 s13, s25, 1
	v_lshl_or_b32 v152, s26, 8, v159
	v_lshl_add_u32 v148, s13, 10, v157
	v_lshl_add_u32 v172, s24, 8, v1
	ds_read2_b32 v[164:165], v148 offset1:16
	ds_read2_b32 v[166:167], v148 offset0:32 offset1:48
	ds_read2_b32 v[154:155], v148 offset0:128 offset1:144
	ds_read2_b32 v[148:149], v148 offset0:160 offset1:176
	v_ashrrev_i32_e32 v153, 31, v152
	v_mov_b64_e32 v[150:151], s[6:7]
	v_mad_i64_i32 v[168:169], s[24:25], v172, s50, v[150:151]
	v_lshlrev_b64 v[152:153], 1, v[152:153]
	v_lshl_add_u64 v[168:169], v[168:169], 0, v[152:153]
	s_waitcnt lgkmcnt(0)
	v_pk_mul_f32 v[128:129], v[128:129], v[164:165] op_sel_hi:[1,0]
	v_pk_mul_f32 v[126:127], v[126:127], v[164:165] op_sel_hi:[1,0]
	v_pk_mul_f32 v[170:171], v[124:125], v[164:165] op_sel_hi:[1,0]
	v_pk_mul_f32 v[124:125], v[122:123], v[164:165] op_sel_hi:[1,0]
	v_cvt_pk_bf16_f32 v122, v126, v127
	v_cvt_pk_bf16_f32 v123, v128, v129
	v_pk_mul_f32 v[118:119], v[118:119], v[164:165] op_sel_hi:[1,0]
	v_cvt_pk_bf16_f32 v124, v124, v125
	v_cvt_pk_bf16_f32 v125, v170, v171
	global_store_dwordx4 v[168:169], v[122:125], off
	v_pk_mul_f32 v[120:121], v[120:121], v[164:165] op_sel_hi:[1,0]
	v_pk_mul_f32 v[98:99], v[98:99], v[166:167] op_sel_hi:[1,0]
	v_pk_mul_f32 v[122:123], v[112:113], v[164:165] op_sel_hi:[1,0]
	v_pk_mul_f32 v[112:113], v[110:111], v[164:165] op_sel_hi:[1,0]
	v_cvt_pk_bf16_f32 v110, v118, v119
	v_cvt_pk_bf16_f32 v111, v120, v121
	v_pk_mul_f32 v[86:87], v[86:87], v[166:167] op_sel_hi:[1,0]
	v_cvt_pk_bf16_f32 v112, v112, v113
	v_cvt_pk_bf16_f32 v113, v122, v123
	global_store_dwordx4 v[168:169], v[110:113], off offset:256
	v_pk_mul_f32 v[88:89], v[88:89], v[166:167] op_sel_hi:[1,0]
	v_pk_mul_f32 v[64:65], v[64:65], v[154:155] op_sel_hi:[1,0]
	v_or_b32_e32 v110, 16, v172
	v_mad_i64_i32 v[110:111], s[24:25], v110, s50, v[150:151]
	v_mov_b32_e32 v112, v165
	v_lshl_add_u64 v[110:111], v[110:111], 0, v[152:153]
	v_pk_mul_f32 v[116:117], v[116:117], v[112:113] op_sel_hi:[1,0]
	v_pk_mul_f32 v[114:115], v[114:115], v[112:113] op_sel_hi:[1,0]
	v_pk_mul_f32 v[118:119], v[108:109], v[112:113] op_sel_hi:[1,0]
	v_pk_mul_f32 v[108:109], v[106:107], v[112:113] op_sel_hi:[1,0]
	v_cvt_pk_bf16_f32 v106, v114, v115
	v_cvt_pk_bf16_f32 v107, v116, v117
	v_pk_mul_f32 v[102:103], v[102:103], v[112:113] op_sel_hi:[1,0]
	v_cvt_pk_bf16_f32 v108, v108, v109
	v_cvt_pk_bf16_f32 v109, v118, v119
	global_store_dwordx4 v[110:111], v[106:109], off
	v_pk_mul_f32 v[104:105], v[104:105], v[112:113] op_sel_hi:[1,0]
	v_pk_mul_f32 v[62:63], v[62:63], v[154:155] op_sel_hi:[1,0]
	v_pk_mul_f32 v[106:107], v[96:97], v[112:113] op_sel_hi:[1,0]
	v_pk_mul_f32 v[96:97], v[94:95], v[112:113] op_sel_hi:[1,0]
	v_cvt_pk_bf16_f32 v94, v102, v103
	v_cvt_pk_bf16_f32 v95, v104, v105
	v_pk_mul_f32 v[54:55], v[54:55], v[154:155] op_sel_hi:[1,0]
	v_cvt_pk_bf16_f32 v96, v96, v97
	v_cvt_pk_bf16_f32 v97, v106, v107
	global_store_dwordx4 v[110:111], v[94:97], off offset:256
	v_pk_mul_f32 v[56:57], v[56:57], v[154:155] op_sel_hi:[1,0]
	v_pk_mul_f32 v[34:35], v[34:35], v[148:149] op_sel_hi:[1,0]
	v_or_b32_e32 v94, 32, v172
	v_mad_i64_i32 v[94:95], s[24:25], v94, s50, v[150:151]
	v_lshl_add_u64 v[94:95], v[94:95], 0, v[152:153]
	v_pk_mul_f32 v[96:97], v[100:101], v[166:167] op_sel_hi:[1,0]
	v_pk_mul_f32 v[100:101], v[92:93], v[166:167] op_sel_hi:[1,0]
	v_pk_mul_f32 v[92:93], v[90:91], v[166:167] op_sel_hi:[1,0]
	v_cvt_pk_bf16_f32 v90, v98, v99
	v_cvt_pk_bf16_f32 v91, v96, v97
	v_pk_mul_f32 v[22:23], v[22:23], v[148:149] op_sel_hi:[1,0]
	v_cvt_pk_bf16_f32 v92, v92, v93
	v_cvt_pk_bf16_f32 v93, v100, v101
	global_store_dwordx4 v[94:95], v[90:93], off
	v_pk_mul_f32 v[24:25], v[24:25], v[148:149] op_sel_hi:[1,0]
	s_nop 0
	v_pk_mul_f32 v[90:91], v[80:81], v[166:167] op_sel_hi:[1,0]
	v_pk_mul_f32 v[80:81], v[78:79], v[166:167] op_sel_hi:[1,0]
	v_cvt_pk_bf16_f32 v78, v86, v87
	v_cvt_pk_bf16_f32 v79, v88, v89
	s_nop 0
	v_cvt_pk_bf16_f32 v80, v80, v81
	v_cvt_pk_bf16_f32 v81, v90, v91
	global_store_dwordx4 v[94:95], v[78:81], off offset:256
	s_nop 1
	v_or_b32_e32 v78, 48, v172
	v_mad_i64_i32 v[78:79], s[24:25], v78, s50, v[150:151]
	v_mov_b32_e32 v80, v167
	v_lshl_add_u64 v[78:79], v[78:79], 0, v[152:153]
	v_pk_mul_f32 v[84:85], v[84:85], v[80:81] op_sel_hi:[1,0]
	v_pk_mul_f32 v[82:83], v[82:83], v[80:81] op_sel_hi:[1,0]
	v_pk_mul_f32 v[86:87], v[76:77], v[80:81] op_sel_hi:[1,0]
	v_pk_mul_f32 v[76:77], v[74:75], v[80:81] op_sel_hi:[1,0]
	v_cvt_pk_bf16_f32 v74, v82, v83
	v_cvt_pk_bf16_f32 v75, v84, v85
	v_pk_mul_f32 v[70:71], v[70:71], v[80:81] op_sel_hi:[1,0]
; __device__ __forceinline__ unsigned cvt_pk_bf16(float lo, float hi) { unsigned r; asm volatile("v_cvt_pk_bf16_f32 %0, %1, %2" : "=v"(r) : "v"(lo), "v"(hi)); return r; }
;     static __device__ __forceinline__ float rstd_of(unsigned long long ss) { return rsqrtf((float)ss * (1.0f / (4096.0f * 16777216.0f)) + 1e-6f); }
;     __device__ __forceinline__ void operator()(const f32x4 (&acc)[2][2][4][2], const Unit& u, int wr, int wc, int fr, int fq, int slot, bool has_next, const Unit& nxt) const {
;     ...
;                 for (int bj = 0; bj < 2; ++bj) { const f32x4 v0 = acc[ai][bj][m][0] * rs, v1 = acc[ai][bj][m][1] * rs;
;                     u32x4 w; w.x = cvt_pk_bf16(v0[0], v0[1]); w.y = cvt_pk_bf16(v0[2], v0[3]); w.z = cvt_pk_bf16(v1[0], v1[1]); w.w = cvt_pk_bf16(v1[2], v1[3]);
;                     *(u32x4*)(rowp + bj * HALF) = w; } }
;         if (fill) tab[(slot ^ 1) * 256 + threadIdx.x] = rstd_of(ssn);
	v_cvt_pk_bf16_f32 v76, v76, v77
	v_cvt_pk_bf16_f32 v77, v86, v87
	global_store_dwordx4 v[78:79], v[74:77], off
	v_pk_mul_f32 v[72:73], v[72:73], v[80:81] op_sel_hi:[1,0]
	s_nop 0
	v_pk_mul_f32 v[74:75], v[68:69], v[80:81] op_sel_hi:[1,0]
	v_pk_mul_f32 v[68:69], v[66:67], v[80:81] op_sel_hi:[1,0]
	v_cvt_pk_bf16_f32 v66, v70, v71
	v_cvt_pk_bf16_f32 v67, v72, v73
	s_nop 0
	v_cvt_pk_bf16_f32 v68, v68, v69
	v_cvt_pk_bf16_f32 v69, v74, v75
	global_store_dwordx4 v[78:79], v[66:69], off offset:256
	s_nop 1
	v_add_u32_e32 v66, 0x80, v172
	v_mad_i64_i32 v[66:67], s[24:25], v66, s50, v[150:151]
	v_lshl_add_u64 v[66:67], v[66:67], 0, v[152:153]
	v_pk_mul_f32 v[68:69], v[60:61], v[154:155] op_sel_hi:[1,0]
	v_pk_mul_f32 v[60:61], v[58:59], v[154:155] op_sel_hi:[1,0]
	v_cvt_pk_bf16_f32 v58, v62, v63
	v_cvt_pk_bf16_f32 v59, v64, v65
	s_nop 0
	v_cvt_pk_bf16_f32 v60, v60, v61
	v_cvt_pk_bf16_f32 v61, v68, v69
	global_store_dwordx4 v[66:67], v[58:61], off
	s_nop 1
	v_pk_mul_f32 v[58:59], v[48:49], v[154:155] op_sel_hi:[1,0]
	v_pk_mul_f32 v[48:49], v[46:47], v[154:155] op_sel_hi:[1,0]
	v_cvt_pk_bf16_f32 v46, v54, v55
	v_cvt_pk_bf16_f32 v47, v56, v57
	s_nop 0
	v_cvt_pk_bf16_f32 v48, v48, v49
	v_cvt_pk_bf16_f32 v49, v58, v59
	global_store_dwordx4 v[66:67], v[46:49], off offset:256
	s_nop 1
	v_add_u32_e32 v46, 0x90, v172
	v_mad_i64_i32 v[46:47], s[24:25], v46, s50, v[150:151]
	v_mov_b32_e32 v48, v155
	v_lshl_add_u64 v[46:47], v[46:47], 0, v[152:153]
	v_pk_mul_f32 v[52:53], v[52:53], v[48:49] op_sel_hi:[1,0]
	v_pk_mul_f32 v[50:51], v[50:51], v[48:49] op_sel_hi:[1,0]
	v_pk_mul_f32 v[54:55], v[44:45], v[48:49] op_sel_hi:[1,0]
	v_pk_mul_f32 v[44:45], v[42:43], v[48:49] op_sel_hi:[1,0]
	v_cvt_pk_bf16_f32 v42, v50, v51
	v_cvt_pk_bf16_f32 v43, v52, v53
	v_pk_mul_f32 v[38:39], v[38:39], v[48:49] op_sel_hi:[1,0]
	v_cvt_pk_bf16_f32 v44, v44, v45
	v_cvt_pk_bf16_f32 v45, v54, v55
	global_store_dwordx4 v[46:47], v[42:45], off
	v_pk_mul_f32 v[40:41], v[40:41], v[48:49] op_sel_hi:[1,0]
	s_nop 0
	v_pk_mul_f32 v[42:43], v[32:33], v[48:49] op_sel_hi:[1,0]
	v_pk_mul_f32 v[32:33], v[30:31], v[48:49] op_sel_hi:[1,0]
	v_cvt_pk_bf16_f32 v30, v38, v39
	v_cvt_pk_bf16_f32 v31, v40, v41
	s_nop 0
	v_cvt_pk_bf16_f32 v32, v32, v33
	v_cvt_pk_bf16_f32 v33, v42, v43
	global_store_dwordx4 v[46:47], v[30:33], off offset:256
	s_nop 1
	v_add_u32_e32 v30, 0xa0, v172
	v_mad_i64_i32 v[30:31], s[24:25], v30, s50, v[150:151]
	v_lshl_add_u64 v[30:31], v[30:31], 0, v[152:153]
	v_pk_mul_f32 v[32:33], v[36:37], v[148:149] op_sel_hi:[1,0]
	v_pk_mul_f32 v[36:37], v[28:29], v[148:149] op_sel_hi:[1,0]
	v_pk_mul_f32 v[28:29], v[26:27], v[148:149] op_sel_hi:[1,0]
	v_cvt_pk_bf16_f32 v26, v34, v35
	v_cvt_pk_bf16_f32 v27, v32, v33
	s_nop 0
	v_cvt_pk_bf16_f32 v28, v28, v29
	v_cvt_pk_bf16_f32 v29, v36, v37
	global_store_dwordx4 v[30:31], v[26:29], off
	s_nop 1
	v_pk_mul_f32 v[26:27], v[16:17], v[148:149] op_sel_hi:[1,0]
	v_pk_mul_f32 v[16:17], v[14:15], v[148:149] op_sel_hi:[1,0]
	v_cvt_pk_bf16_f32 v14, v22, v23
	v_cvt_pk_bf16_f32 v15, v24, v25
	s_nop 0
	v_cvt_pk_bf16_f32 v16, v16, v17
	v_cvt_pk_bf16_f32 v17, v26, v27
	global_store_dwordx4 v[30:31], v[14:17], off offset:256
	s_nop 1
	v_add_u32_e32 v14, 0xb0, v172
	v_mad_i64_i32 v[14:15], s[24:25], v14, s50, v[150:151]
	v_mov_b32_e32 v16, v149
	v_lshl_add_u64 v[14:15], v[14:15], 0, v[152:153]
	v_pk_mul_f32 v[20:21], v[20:21], v[16:17] op_sel_hi:[1,0]
	v_pk_mul_f32 v[18:19], v[18:19], v[16:17] op_sel_hi:[1,0]
	v_pk_mul_f32 v[22:23], v[12:13], v[16:17] op_sel_hi:[1,0]
	v_pk_mul_f32 v[12:13], v[10:11], v[16:17] op_sel_hi:[1,0]
	v_cvt_pk_bf16_f32 v10, v18, v19
	v_cvt_pk_bf16_f32 v11, v20, v21
	v_pk_mul_f32 v[8:9], v[8:9], v[16:17] op_sel_hi:[1,0]
	v_cvt_pk_bf16_f32 v12, v12, v13
	v_cvt_pk_bf16_f32 v13, v22, v23
	global_store_dwordx4 v[14:15], v[10:13], off
	v_pk_mul_f32 v[6:7], v[6:7], v[16:17] op_sel_hi:[1,0]
	s_nop 0
	v_pk_mul_f32 v[10:11], v[4:5], v[16:17] op_sel_hi:[1,0]
	v_pk_mul_f32 v[4:5], v[2:3], v[16:17] op_sel_hi:[1,0]
	v_cvt_pk_bf16_f32 v2, v6, v7
	v_cvt_pk_bf16_f32 v3, v8, v9
	s_nop 0
	v_cvt_pk_bf16_f32 v4, v4, v5
	v_cvt_pk_bf16_f32 v5, v10, v11
	global_store_dwordx4 v[14:15], v[2:5], off offset:256
	s_and_saveexec_b64 s[24:25], s[28:29]
	s_cbranch_execz .LBB0_195
	s_waitcnt vmcnt(16)
	v_ffbh_u32_e32 v138, v245
	v_min_u32_e32 v138, 32, v138
	v_lshlrev_b64 v[244:245], v138, v[244:245]
	v_min_u32_e32 v244, 1, v244
	v_or_b32_e32 v244, v245, v244
	v_cvt_f32_u32_e32 v244, v244
	v_sub_u32_e32 v138, 32, v138
	v_ldexp_f32 v138, v244, v138
	v_fmamk_f32 v138, v138, 0x2d800000, v163
	v_mul_f32_e32 v2, 0x4b800000, v138
	v_cmp_gt_f32_e32 vcc, s51, v138
	s_lshl_b32 s13, s13, 10
	s_xor_b32 s13, s13, 0x400
	v_cndmask_b32_e32 v2, v138, v2, vcc
	v_rsq_f32_e32 v2, v2
	s_nop 0
	v_mul_f32_e32 v3, 0x45800000, v2
	v_cndmask_b32_e32 v2, v2, v3, vcc
	v_add_u32_e32 v3, s13, v158
	ds_write_b32 v3, v2

; __device__ __forceinline__ unsigned cvt_pk_bf16(float lo, float hi) { unsigned r; asm volatile("v_cvt_pk_bf16_f32 %0, %1, %2" : "=v"(r) : "v"(lo), "v"(hi)); return r; }
;     __device__ __forceinline__ void operator()(const f32x4 (&acc)[2][2][4][2], const Unit& u, int wr, int wc, int fr, int fq, int slot, bool has_next, const Unit& nxt) const {
;         const int row0 = u.pm * BM + wr * 64 + fr, col0 = u.pn * BM + wc * 32 + 8 * fq;
;         const bool fill = has_next && threadIdx.x < 256;
;         unsigned long long ssn = 0; if (fill) ssn = rowss[nxt.pm * BM + threadIdx.x];
;         float rsv[8];
; #pragma unroll
;         for (int i = 0; i < 8; ++i) rsv[i] = tab[slot * 256 + wr * 64 + fr + (i >> 2) * HALF + (i & 3) * 16];
; #pragma unroll
;         for (int ai = 0; ai < 2; ++ai)
; #pragma unroll
;             for (int m = 0; m < 4; ++m) { const int row = row0 + ai * HALF + m * 16; const float rs = rsv[ai * 4 + m];
;                 bf16_t* rowp = O + (size_t)row * ldc + col0;
; #pragma unroll
;                 for (int bj = 0; bj < 2; ++bj) { const f32x4 v0 = acc[ai][bj][m][0] * rs, v1 = acc[ai][bj][m][1] * rs;
;                     u32x4 w; w.x = cvt_pk_bf16(v0[0], v0[1]); w.y = cvt_pk_bf16(v0[2], v0[3]); w.z = cvt_pk_bf16(v1[0], v1[1]); w.w = cvt_pk_bf16(v1[2], v1[3]);
;                     *(u32x4*)(rowp + bj * HALF) = w; } }
.LBB0_744:
	s_and_b64 s[38:39], s[0:1], s[2:3]
	v_mov_b32_e32 v138, 0x358637bd
	s_and_saveexec_b64 s[40:41], s[38:39]
	s_cbranch_execz .LBB0_746
	v_lshl_or_b32 v138, s26, 8, v0
	v_lshl_add_u64 v[244:245], v[138:139], 3, s[6:7]
	global_load_dwordx2 v[244:245], v[244:245], off
.LBB0_746:
	s_or_b64 exec, exec, s[40:41]
	s_and_b32 s25, s35, 1
	v_lshl_add_u32 v162, s34, 8, v1
	v_lshl_or_b32 v148, s36, 8, v157
	v_lshl_add_u32 v149, s25, 10, v155
	v_ashrrev_i32_e32 v163, 31, v162
	ds_read2_b32 v[164:165], v149 offset1:16
	ds_read2_b32 v[166:167], v149 offset0:32 offset1:48
	ds_read2_b32 v[152:153], v149 offset0:128 offset1:144
	ds_read2_b32 v[150:151], v149 offset0:160 offset1:176
	v_ashrrev_i32_e32 v149, 31, v148
	v_lshlrev_b64 v[168:169], 15, v[162:163]
	v_lshl_add_u64 v[168:169], s[10:11], 0, v[168:169]
	v_lshlrev_b64 v[170:171], 1, v[148:149]
	v_lshl_add_u64 v[148:149], v[168:169], 0, v[170:171]
	s_waitcnt lgkmcnt(0)
	v_pk_mul_f32 v[128:129], v[128:129], v[164:165] op_sel_hi:[1,0]
	v_pk_mul_f32 v[126:127], v[126:127], v[164:165] op_sel_hi:[1,0]
	v_pk_mul_f32 v[168:169], v[124:125], v[164:165] op_sel_hi:[1,0]
	v_pk_mul_f32 v[124:125], v[122:123], v[164:165] op_sel_hi:[1,0]
	v_cvt_pk_bf16_f32 v122, v126, v127
	v_cvt_pk_bf16_f32 v123, v128, v129
	v_pk_mul_f32 v[118:119], v[118:119], v[164:165] op_sel_hi:[1,0]
	v_cvt_pk_bf16_f32 v124, v124, v125
	v_cvt_pk_bf16_f32 v125, v168, v169
	global_store_dwordx4 v[148:149], v[122:125], off
	v_pk_mul_f32 v[120:121], v[120:121], v[164:165] op_sel_hi:[1,0]
	v_pk_mul_f32 v[96:97], v[96:97], v[166:167] op_sel_hi:[1,0]
	v_pk_mul_f32 v[122:123], v[116:117], v[164:165] op_sel_hi:[1,0]
	v_pk_mul_f32 v[116:117], v[114:115], v[164:165] op_sel_hi:[1,0]
	v_cvt_pk_bf16_f32 v114, v118, v119
	v_cvt_pk_bf16_f32 v115, v120, v121
	v_pk_mul_f32 v[94:95], v[94:95], v[166:167] op_sel_hi:[1,0]
	v_cvt_pk_bf16_f32 v116, v116, v117
	v_cvt_pk_bf16_f32 v117, v122, v123
	global_store_dwordx4 v[148:149], v[114:117], off offset:256
	v_pk_mul_f32 v[86:87], v[86:87], v[166:167] op_sel_hi:[1,0]
	v_pk_mul_f32 v[88:89], v[88:89], v[166:167] op_sel_hi:[1,0]
	v_or_b32_e32 v114, 16, v162
	v_ashrrev_i32_e32 v115, 31, v114
	v_lshlrev_b64 v[114:115], 15, v[114:115]
	v_lshl_add_u64 v[114:115], s[10:11], 0, v[114:115]
	v_mov_b32_e32 v116, v165
	v_lshl_add_u64 v[114:115], v[114:115], 0, v[170:171]
	v_pk_mul_f32 v[112:113], v[112:113], v[116:117] op_sel_hi:[1,0]
	v_pk_mul_f32 v[110:111], v[110:111], v[116:117] op_sel_hi:[1,0]
	v_pk_mul_f32 v[118:119], v[108:109], v[116:117] op_sel_hi:[1,0]
	v_pk_mul_f32 v[108:109], v[106:107], v[116:117] op_sel_hi:[1,0]
	v_cvt_pk_bf16_f32 v106, v110, v111
	v_cvt_pk_bf16_f32 v107, v112, v113
	v_pk_mul_f32 v[102:103], v[102:103], v[116:117] op_sel_hi:[1,0]
	v_cvt_pk_bf16_f32 v108, v108, v109
	v_cvt_pk_bf16_f32 v109, v118, v119
	global_store_dwordx4 v[114:115], v[106:109], off
	v_pk_mul_f32 v[104:105], v[104:105], v[116:117] op_sel_hi:[1,0]
	v_pk_mul_f32 v[62:63], v[62:63], v[152:153] op_sel_hi:[1,0]
	v_pk_mul_f32 v[106:107], v[100:101], v[116:117] op_sel_hi:[1,0]
	v_pk_mul_f32 v[100:101], v[98:99], v[116:117] op_sel_hi:[1,0]
	v_cvt_pk_bf16_f32 v98, v102, v103
	v_cvt_pk_bf16_f32 v99, v104, v105
	v_pk_mul_f32 v[64:65], v[64:65], v[152:153] op_sel_hi:[1,0]
	v_cvt_pk_bf16_f32 v100, v100, v101
	v_cvt_pk_bf16_f32 v101, v106, v107
	global_store_dwordx4 v[114:115], v[98:101], off offset:256
	v_pk_mul_f32 v[56:57], v[56:57], v[152:153] op_sel_hi:[1,0]
	v_pk_mul_f32 v[54:55], v[54:55], v[152:153] op_sel_hi:[1,0]
	v_or_b32_e32 v98, 32, v162
	v_ashrrev_i32_e32 v99, 31, v98
	v_lshlrev_b64 v[98:99], 15, v[98:99]
	v_lshl_add_u64 v[98:99], s[10:11], 0, v[98:99]
	v_lshl_add_u64 v[98:99], v[98:99], 0, v[170:171]
	v_pk_mul_f32 v[100:101], v[92:93], v[166:167] op_sel_hi:[1,0]
	v_pk_mul_f32 v[92:93], v[90:91], v[166:167] op_sel_hi:[1,0]
	v_cvt_pk_bf16_f32 v90, v94, v95
	v_cvt_pk_bf16_f32 v91, v96, v97
	v_pk_mul_f32 v[34:35], v[34:35], v[150:151] op_sel_hi:[1,0]
	v_cvt_pk_bf16_f32 v92, v92, v93
	v_cvt_pk_bf16_f32 v93, v100, v101
	global_store_dwordx4 v[98:99], v[90:93], off
	v_pk_mul_f32 v[24:25], v[24:25], v[150:151] op_sel_hi:[1,0]
	v_pk_mul_f32 v[22:23], v[22:23], v[150:151] op_sel_hi:[1,0]
	v_pk_mul_f32 v[90:91], v[84:85], v[166:167] op_sel_hi:[1,0]
	v_pk_mul_f32 v[84:85], v[82:83], v[166:167] op_sel_hi:[1,0]
	v_cvt_pk_bf16_f32 v82, v86, v87
	v_cvt_pk_bf16_f32 v83, v88, v89
	s_nop 0
	v_cvt_pk_bf16_f32 v84, v84, v85
	v_cvt_pk_bf16_f32 v85, v90, v91
	global_store_dwordx4 v[98:99], v[82:85], off offset:256
	s_nop 1
	v_or_b32_e32 v82, 48, v162
	v_ashrrev_i32_e32 v83, 31, v82
	v_lshlrev_b64 v[82:83], 15, v[82:83]
	v_lshl_add_u64 v[82:83], s[10:11], 0, v[82:83]
	v_mov_b32_e32 v84, v167
	v_lshl_add_u64 v[82:83], v[82:83], 0, v[170:171]
	v_pk_mul_f32 v[80:81], v[80:81], v[84:85] op_sel_hi:[1,0]
	v_pk_mul_f32 v[78:79], v[78:79], v[84:85] op_sel_hi:[1,0]
	v_pk_mul_f32 v[86:87], v[76:77], v[84:85] op_sel_hi:[1,0]
	v_pk_mul_f32 v[76:77], v[74:75], v[84:85] op_sel_hi:[1,0]
; __device__ __forceinline__ unsigned cvt_pk_bf16(float lo, float hi) { unsigned r; asm volatile("v_cvt_pk_bf16_f32 %0, %1, %2" : "=v"(r) : "v"(lo), "v"(hi)); return r; }
;     static __device__ __forceinline__ float rstd_of(unsigned long long ss) { return rsqrtf((float)ss * (1.0f / (4096.0f * 16777216.0f)) + 1e-6f); }
;     __device__ __forceinline__ void operator()(const f32x4 (&acc)[2][2][4][2], const Unit& u, int wr, int wc, int fr, int fq, int slot, bool has_next, const Unit& nxt) const {
;     ...
;             for (int m = 0; m < 4; ++m) { const int row = row0 + ai * HALF + m * 16; const float rs = rsv[ai * 4 + m];
;                 bf16_t* rowp = O + (size_t)row * ldc + col0;
; #pragma unroll
;                 for (int bj = 0; bj < 2; ++bj) { const f32x4 v0 = acc[ai][bj][m][0] * rs, v1 = acc[ai][bj][m][1] * rs;
;                     u32x4 w; w.x = cvt_pk_bf16(v0[0], v0[1]); w.y = cvt_pk_bf16(v0[2], v0[3]); w.z = cvt_pk_bf16(v1[0], v1[1]); w.w = cvt_pk_bf16(v1[2], v1[3]);
;                     *(u32x4*)(rowp + bj * HALF) = w; } }
;         if (fill) tab[(slot ^ 1) * 256 + threadIdx.x] = rstd_of(ssn);
	v_cvt_pk_bf16_f32 v74, v78, v79
	v_cvt_pk_bf16_f32 v75, v80, v81
	v_pk_mul_f32 v[72:73], v[72:73], v[84:85] op_sel_hi:[1,0]
	v_cvt_pk_bf16_f32 v76, v76, v77
	v_cvt_pk_bf16_f32 v77, v86, v87
	global_store_dwordx4 v[82:83], v[74:77], off
	v_pk_mul_f32 v[70:71], v[70:71], v[84:85] op_sel_hi:[1,0]
	s_nop 0
	v_pk_mul_f32 v[74:75], v[68:69], v[84:85] op_sel_hi:[1,0]
	v_pk_mul_f32 v[68:69], v[66:67], v[84:85] op_sel_hi:[1,0]
	v_cvt_pk_bf16_f32 v66, v70, v71
	v_cvt_pk_bf16_f32 v67, v72, v73
	s_nop 0
	v_cvt_pk_bf16_f32 v68, v68, v69
	v_cvt_pk_bf16_f32 v69, v74, v75
	global_store_dwordx4 v[82:83], v[66:69], off offset:256
	s_nop 1
	v_pk_mul_f32 v[68:69], v[60:61], v[152:153] op_sel_hi:[1,0]
	v_pk_mul_f32 v[60:61], v[58:59], v[152:153] op_sel_hi:[1,0]
	v_cvt_pk_bf16_f32 v58, v62, v63
	v_add_co_u32_e32 v62, vcc, s57, v148
	v_cvt_pk_bf16_f32 v59, v64, v65
	v_cvt_pk_bf16_f32 v60, v60, v61
	v_cvt_pk_bf16_f32 v61, v68, v69
	v_lshl_add_u64 v[66:67], v[148:149], 0, s[16:17]
	s_nop 0
	v_addc_co_u32_e32 v63, vcc, 0, v149, vcc
	global_store_dwordx4 v[62:63], v[58:61], off
	s_nop 1
	v_pk_mul_f32 v[58:59], v[48:49], v[152:153] op_sel_hi:[1,0]
	v_pk_mul_f32 v[48:49], v[46:47], v[152:153] op_sel_hi:[1,0]
	v_cvt_pk_bf16_f32 v46, v54, v55
	v_cvt_pk_bf16_f32 v47, v56, v57
	s_nop 0
	v_cvt_pk_bf16_f32 v48, v48, v49
	v_cvt_pk_bf16_f32 v49, v58, v59
	global_store_dwordx4 v[66:67], v[46:49], off offset:256
	s_nop 1
	v_mov_b32_e32 v48, v153
	v_pk_mul_f32 v[50:51], v[50:51], v[48:49] op_sel_hi:[1,0]
	v_pk_mul_f32 v[54:55], v[44:45], v[48:49] op_sel_hi:[1,0]
	v_pk_mul_f32 v[44:45], v[42:43], v[48:49] op_sel_hi:[1,0]
	v_cvt_pk_bf16_f32 v42, v50, v51
	v_add_co_u32_e32 v50, vcc, s58, v148
	v_pk_mul_f32 v[52:53], v[52:53], v[48:49] op_sel_hi:[1,0]
	s_nop 0
	v_addc_co_u32_e32 v51, vcc, 0, v149, vcc
	v_cvt_pk_bf16_f32 v43, v52, v53
	v_cvt_pk_bf16_f32 v44, v44, v45
	v_cvt_pk_bf16_f32 v45, v54, v55
	global_store_dwordx4 v[50:51], v[42:45], off
	v_lshl_add_u64 v[46:47], v[148:149], 0, s[18:19]
	v_pk_mul_f32 v[40:41], v[40:41], v[48:49] op_sel_hi:[1,0]
	v_pk_mul_f32 v[42:43], v[32:33], v[48:49] op_sel_hi:[1,0]
	v_pk_mul_f32 v[32:33], v[30:31], v[48:49] op_sel_hi:[1,0]
	v_pk_mul_f32 v[38:39], v[38:39], v[48:49] op_sel_hi:[1,0]
	s_nop 0
	v_cvt_pk_bf16_f32 v30, v38, v39
	v_cvt_pk_bf16_f32 v31, v40, v41
	v_cvt_pk_bf16_f32 v32, v32, v33
	v_cvt_pk_bf16_f32 v33, v42, v43
	global_store_dwordx4 v[46:47], v[30:33], off offset:256
	s_nop 1
	v_pk_mul_f32 v[32:33], v[36:37], v[150:151] op_sel_hi:[1,0]
	v_pk_mul_f32 v[36:37], v[28:29], v[150:151] op_sel_hi:[1,0]
	v_pk_mul_f32 v[28:29], v[26:27], v[150:151] op_sel_hi:[1,0]
	v_cvt_pk_bf16_f32 v26, v34, v35
	v_cvt_pk_bf16_f32 v27, v32, v33
	v_add_co_u32_e32 v32, vcc, s59, v148
	v_cvt_pk_bf16_f32 v28, v28, v29
	v_cvt_pk_bf16_f32 v29, v36, v37
	v_lshl_add_u64 v[30:31], v[148:149], 0, s[20:21]
	s_nop 0
	v_addc_co_u32_e32 v33, vcc, 0, v149, vcc
	global_store_dwordx4 v[32:33], v[26:29], off
	s_nop 1
	v_pk_mul_f32 v[26:27], v[16:17], v[150:151] op_sel_hi:[1,0]
	v_pk_mul_f32 v[16:17], v[14:15], v[150:151] op_sel_hi:[1,0]
	v_cvt_pk_bf16_f32 v14, v22, v23
	v_cvt_pk_bf16_f32 v15, v24, v25
	s_nop 0
	v_cvt_pk_bf16_f32 v16, v16, v17
	v_cvt_pk_bf16_f32 v17, v26, v27
	global_store_dwordx4 v[30:31], v[14:17], off offset:256
	s_nop 1
	v_mov_b32_e32 v16, v151
	v_pk_mul_f32 v[18:19], v[18:19], v[16:17] op_sel_hi:[1,0]
	v_pk_mul_f32 v[22:23], v[12:13], v[16:17] op_sel_hi:[1,0]
	v_pk_mul_f32 v[12:13], v[10:11], v[16:17] op_sel_hi:[1,0]
	v_cvt_pk_bf16_f32 v10, v18, v19
	v_add_co_u32_e32 v18, vcc, s60, v148
	v_pk_mul_f32 v[20:21], v[20:21], v[16:17] op_sel_hi:[1,0]
	s_nop 0
	v_addc_co_u32_e32 v19, vcc, 0, v149, vcc
	v_cvt_pk_bf16_f32 v11, v20, v21
	v_lshl_add_u64 v[14:15], v[148:149], 0, s[22:23]
	v_cvt_pk_bf16_f32 v12, v12, v13
	v_cvt_pk_bf16_f32 v13, v22, v23
	global_store_dwordx4 v[18:19], v[10:13], off
	v_pk_mul_f32 v[8:9], v[8:9], v[16:17] op_sel_hi:[1,0]
	v_pk_mul_f32 v[6:7], v[6:7], v[16:17] op_sel_hi:[1,0]
	v_pk_mul_f32 v[10:11], v[4:5], v[16:17] op_sel_hi:[1,0]
	v_pk_mul_f32 v[4:5], v[2:3], v[16:17] op_sel_hi:[1,0]
	v_cvt_pk_bf16_f32 v2, v6, v7
	v_cvt_pk_bf16_f32 v3, v8, v9
	s_nop 0
	v_cvt_pk_bf16_f32 v4, v4, v5
	v_cvt_pk_bf16_f32 v5, v10, v11
	global_store_dwordx4 v[14:15], v[2:5], off offset:256
	s_and_saveexec_b64 s[34:35], s[38:39]
	s_cbranch_execz .LBB0_748
	s_waitcnt vmcnt(16)
	v_ffbh_u32_e32 v138, v245
	v_min_u32_e32 v138, 32, v138
	v_lshlrev_b64 v[244:245], v138, v[244:245]
	v_min_u32_e32 v244, 1, v244
	v_or_b32_e32 v244, v245, v244
	v_cvt_f32_u32_e32 v244, v244
	v_sub_u32_e32 v138, 32, v138
	v_ldexp_f32 v138, v244, v138
	v_fmamk_f32 v138, v138, 0x2d800000, v161
	v_mul_f32_e32 v2, 0x4b800000, v138
	v_cmp_gt_f32_e32 vcc, s61, v138
	s_lshl_b32 s25, s25, 10
	s_xor_b32 s25, s25, 0x400
	v_cndmask_b32_e32 v2, v138, v2, vcc
	v_rsq_f32_e32 v2, v2
	s_nop 0
	v_mul_f32_e32 v3, 0x45800000, v2
	v_cndmask_b32_e32 v2, v2, v3, vcc
	v_add_u32_e32 v3, s25, v156
	ds_write_b32 v3, v2
